# waves 4-7 at static priority 1 during the attention phases (layer 0 and layer 1)
# baseline (speedup 1.0000x reference)
; __device__ __forceinline__ int crow(int r,int hi){return (r&3)+8*(r>>2)+4*hi;}
; template<int MODE,int THRL> __device__ __forceinline__ void attn_unit(const bf16*Qw0,int PQ,const bf16*__restrict__ Kh,int PK,const bf16*__restrict__ Vh,int PV,bf16*Ow0,int PO,int NT,int nabase,int nar0,const float*rpbh,char*shm,int&rot,bool pre,bool hasn,long dKn,long dVn){
;     ...
;   {auto rr=__builtin_amdgcn_permlane32_swap(__float_as_uint(l_reg),__float_as_uint(l_reg),false,false);l_reg=__uint_as_float(rr[0])+__uint_as_float(rr[1]);}
;   if(hi==0)wsf[32+r32]=l_reg;asm volatile("s_waitcnt lgkmcnt(0)":::"memory");
;   float rli[16];
;   #pragma unroll
;   for(int r=0;r<16;++r)rli[r]=__builtin_amdgcn_rcpf(wsf[32+crow(r,hi)]);
;   bf16*Ow=Ow0+(long)wid*QBLK*PO;
;   { bf16*stg=(bf16*)(shm+LDS_OST)+wid*2048;
;     #pragma unroll
;     for(int hf=0;hf<ND/2;++hf){
;     #pragma unroll
;     for(int r=0;r<16;++r){const int orow=crow(r,hi);
;       #pragma unroll
;       for(int d0=0;d0<2;++d0)stg[orow*64+d0*32+r32]=__float2bfloat16(o[2*hf+d0][r]*rli[r]);}
;     asm volatile("s_waitcnt lgkmcnt(0)":::"memory");
;     #pragma unroll
;     for(int i=0;i<4;++i){const int row=i*8+(lane>>3),ch=lane&7; const u32x4 v=*(const u32x4*)(stg+row*64+ch*8); ATTN_STORE16(Ow+(long)row*PO+hf*64+ch*8,v);}
;     asm volatile("s_waitcnt lgkmcnt(0)":::"memory"); } }
;   rot=sl_next;
;   asm volatile("s_waitcnt lgkmcnt(0)\n\ts_barrier":::"memory");
; template <int l> __device__ __forceinline__ void layer_body(const Args& a, unsigned char* lds, const XcdBarrier& bar, int G, int bx, int vcu, int gw, int NGW, int lane_, int tid_k, int wave) {
;     ...
;                 const int pern = (1024 + G - 1) / G; int rot = 0; bool pre = false;
;                 for (int i = 0; i < pern; ++i) { const int n = vcu * pern + i; if (n >= 1024) break;
;                     const int b = n >> 8, h = (n >> 5) & 7, qb = n & 31; const int r0 = qb * 4; int nb = r0 - 4; nb = nb < 0 ? 0 : (nb > 116 ? 116 : nb);
;                     const size_t rb = (size_t)b * TPB, rq = rb + CTXL + (size_t)qb * 256;
;                     const int n2 = n + 1; const bool hasn = (i + 1 < pern) && (n2 < 1024); const int b2 = n2 >> 8, h2 = (n2 >> 5) & 7; const size_t rb2 = (size_t)b2 * TPB;
;                     attn_body::attn_unit<1, 8>(qkv + rq * PAR_IN + h * 64, PAR_IN, qkv + rb * PAR_IN + 512 + h * 64, PAR_IN, qkv + rb * PAR_IN + 1024 + h * 64, PAR_IN,
.LBB0_313:
	v_writelane_b32 v254, s38, 8
	s_nop 1
	v_writelane_b32 v254, s39, 9
	v_writelane_b32 v254, s90, 10
	s_nop 1
	v_writelane_b32 v254, s91, 11
	s_or_b64 exec, exec, s[4:5]
	s_abs_i32 s91, s34
	s_waitcnt lgkmcnt(0)
	v_cvt_f32_u32_e32 v0, s91
	s_sub_i32 s3, 0, s91
	s_add_i32 s0, s34, 0x3ff
	s_ashr_i32 s1, s0, 31
	v_rcp_iflag_f32_e32 v0, v0
	s_abs_i32 s0, s0
	s_ashr_i32 s97, s34, 31
	s_xor_b32 s1, s1, s97
	v_mul_f32_e32 v0, 0x4f7ffffe, v0
	v_cvt_u32_f32_e32 v0, v0
	s_mov_b32 s7, 0
	s_barrier
	v_readfirstlane_b32 s4, v0
	s_mul_i32 s3, s3, s4
	s_mul_hi_u32 s3, s4, s3
	s_add_i32 s95, s4, s3
	s_mul_hi_u32 s3, s0, s95
	s_mul_i32 s4, s3, s91
	s_sub_i32 s0, s0, s4
	s_add_i32 s4, s3, 1
	s_sub_i32 s5, s0, s91
	s_cmp_ge_u32 s0, s91
	s_cselect_b32 s3, s4, s3
	s_cselect_b32 s0, s5, s0
	s_add_i32 s4, s3, 1
	s_cmp_ge_u32 s0, s91
	s_cselect_b32 s0, s4, s3
	s_xor_b32 s0, s0, s1
	s_sub_i32 s0, s0, s1
	s_cmp_lt_i32 s0, 1
	s_cbranch_scc1 .LBB0_455
	v_readlane_b32 s1, v254, 0
	s_mul_i32 s1, s0, s1
	s_add_u32 s33, s30, 0x1e7d0000
	s_addc_u32 s39, s31, 0
	s_mov_b64 s[62:63], 0
	v_mov_b32_e32 v0, 0
	s_mov_b64 s[8:9], 0x400
	s_mov_b64 s[10:11], 0x800
	s_mov_b64 s[48:49], 0x48000
	s_mov_b64 s[52:53], 0x90000
	s_mov_b64 s[54:55], 0xd8000
	s_mov_b32 s43, 0x41000000
	v_mov_b32_e32 v232, 0x78
	v_mov_b32_e32 v233, 0x1200
	v_mov_b64_e32 v[224:225], 0x78
	s_mov_b32 s74, s1
	s_mov_b32 s75, 0
	s_mov_b32 s14, 0
	s_cmp_gt_u32 s94, 3
	s_cbranch_scc0 .Lprio_l0
	s_setprio 1
.Lprio_l0:
	s_branch .LBB0_317
.LBB0_315:
	s_or_b64 exec, exec, s[60:61]
	s_waitcnt lgkmcnt(0)
	ds_read_b128 v[34:37], v242 offset:128
	ds_read_b128 v[38:41], v242 offset:160
	s_lshl_b64 s[4:5], s[58:59], 11
	s_add_u32 s3, s46, s4
	s_addc_u32 s4, s47, s5
	s_waitcnt lgkmcnt(1)
	v_rcp_f32_e32 v1, v34
	v_rcp_f32_e32 v42, v35
	v_rcp_f32_e32 v43, v36
	v_rcp_f32_e32 v44, v37
	ds_read_b128 v[34:37], v242 offset:192
	s_add_u32 s3, s3, s76
	s_addc_u32 s6, s4, 0
	s_lshl_b32 s12, s56, 12
	s_waitcnt lgkmcnt(1)
	v_rcp_f32_e32 v45, v38
	v_rcp_f32_e32 v46, v39
	v_rcp_f32_e32 v47, v40
	v_rcp_f32_e32 v48, v41
	ds_read_b128 v[38:41], v242 offset:224
	s_waitcnt lgkmcnt(1)
	v_rcp_f32_e32 v49, v34
	s_add_i32 s12, s12, 0x12800
	v_lshlrev_b32_e32 v34, 1, v236
	v_lshlrev_b32_e32 v50, 9, v237
	v_mul_f32_e32 v2, v2, v1
	v_mul_f32_e32 v1, v18, v1
	v_or3_b32 v50, s12, v34, v50
	v_cvt_pk_bf16_f32 v1, v1, s0
	ds_write_b16 v50, v1 offset:64
	v_mul_f32_e32 v1, v3, v42
	v_cvt_pk_bf16_f32 v1, v1, s0
	ds_write_b16 v50, v1 offset:128
	v_mul_f32_e32 v1, v19, v42
	v_cvt_pk_bf16_f32 v1, v1, s0
	ds_write_b16 v50, v1 offset:192
	v_mul_f32_e32 v1, v4, v43
	v_cvt_pk_bf16_f32 v1, v1, s0
	ds_write_b16 v50, v1 offset:256
	v_mul_f32_e32 v1, v20, v43
	v_cvt_pk_bf16_f32 v1, v1, s0
	ds_write_b16 v50, v1 offset:320
	v_mul_f32_e32 v1, v5, v44
	v_cvt_pk_bf16_f32 v1, v1, s0
	ds_write_b16 v50, v1 offset:384
	v_mul_f32_e32 v1, v21, v44
	v_cvt_pk_bf16_f32 v1, v1, s0
	ds_write_b16 v50, v1 offset:448
	v_mul_f32_e32 v1, v6, v45
	v_cvt_pk_bf16_f32 v1, v1, s0
	ds_write_b16 v50, v1 offset:1024
	v_mul_f32_e32 v1, v22, v45
	v_cvt_pk_bf16_f32 v1, v1, s0
	ds_write_b16 v50, v1 offset:1088
	v_mul_f32_e32 v1, v7, v46
	v_cvt_pk_bf16_f32 v1, v1, s0
	ds_write_b16 v50, v1 offset:1152
	v_mul_f32_e32 v1, v23, v46
	v_cvt_pk_bf16_f32 v1, v1, s0
	ds_write_b16 v50, v1 offset:1216
	v_mul_f32_e32 v1, v8, v47
	v_cvt_pk_bf16_f32 v1, v1, s0
	ds_write_b16 v50, v1 offset:1280
	v_mul_f32_e32 v1, v24, v47
	v_cvt_pk_bf16_f32 v1, v1, s0
	ds_write_b16 v50, v1 offset:1344
	v_mul_f32_e32 v1, v9, v48
	v_cvt_pk_bf16_f32 v1, v1, s0
	ds_write_b16 v50, v1 offset:1408
	v_mul_f32_e32 v1, v25, v48
	v_cvt_pk_bf16_f32 v1, v1, s0
	v_rcp_f32_e32 v35, v35
	ds_write_b16 v50, v1 offset:1472
	v_mul_f32_e32 v1, v10, v49
	v_cvt_pk_bf16_f32 v1, v1, s0
	ds_write_b16 v50, v1 offset:2048
	v_mul_f32_e32 v1, v26, v49
	v_cvt_pk_bf16_f32 v1, v1, s0
	v_rcp_f32_e32 v36, v36
	ds_write_b16 v50, v1 offset:2112
	v_mul_f32_e32 v1, v11, v35
	v_cvt_pk_bf16_f32 v1, v1, s0
	ds_write_b16 v50, v1 offset:2176
	v_mul_f32_e32 v1, v27, v35
	v_cvt_pk_bf16_f32 v1, v1, s0
	v_rcp_f32_e32 v37, v37
	ds_write_b16 v50, v1 offset:2240
	v_mul_f32_e32 v1, v12, v36
	v_cvt_pk_bf16_f32 v1, v1, s0
	ds_write_b16 v50, v1 offset:2304
	v_mul_f32_e32 v1, v28, v36
	v_cvt_pk_bf16_f32 v1, v1, s0
	s_waitcnt lgkmcnt(14)
	v_rcp_f32_e32 v38, v38
	ds_write_b16 v50, v1 offset:2368
	v_mul_f32_e32 v1, v13, v37
	v_cvt_pk_bf16_f32 v1, v1, s0
	ds_write_b16 v50, v1 offset:2432
	v_mul_f32_e32 v1, v29, v37
	v_cvt_pk_bf16_f32 v1, v1, s0
	v_rcp_f32_e32 v39, v39
	ds_write_b16 v50, v1 offset:2496
	v_mul_f32_e32 v1, v14, v38
	v_cvt_pk_bf16_f32 v1, v1, s0
	ds_write_b16 v50, v1 offset:3072
	v_mul_f32_e32 v1, v30, v38
	v_cvt_pk_bf16_f32 v1, v1, s0
	v_rcp_f32_e32 v40, v40
	ds_write_b16 v50, v1 offset:3136
	v_mul_f32_e32 v1, v15, v39
	v_cvt_pk_bf16_f32 v1, v1, s0
	ds_write_b16 v50, v1 offset:3200
	v_mul_f32_e32 v1, v31, v39
	v_cvt_pk_bf16_f32 v1, v1, s0
	v_rcp_f32_e32 v41, v41
	ds_write_b16 v50, v1 offset:3264
	v_mul_f32_e32 v1, v16, v40
	v_cvt_pk_bf16_f32 v1, v1, s0
	ds_write_b16 v50, v1 offset:3328
	v_mul_f32_e32 v1, v32, v40
	v_cvt_pk_bf16_f32 v1, v1, s0
	ds_write_b16 v50, v1 offset:3392
	v_mul_f32_e32 v1, v17, v41
	v_cvt_pk_bf16_f32 v1, v1, s0
	v_lshlrev_b32_e32 v34, 1, v235
	ds_write_b16 v50, v1 offset:3456
	v_mul_f32_e32 v1, v33, v41
	s_lshl_b64 s[4:5], s[56:57], 16
	v_and_b32_e32 v34, 0x70, v34
	v_cvt_pk_bf16_f32 v2, v2, s0
	v_cvt_pk_bf16_f32 v1, v1, s0
	v_or_b32_e32 v51, s12, v34
	ds_write_b16 v50, v2
	ds_write_b16 v50, v1 offset:3520
	s_add_u32 s4, s3, s4
	v_lshrrev_b32_e32 v1, 3, v234
	s_addc_u32 s5, s6, s5
	v_mov_b32_e32 v35, v0
	s_waitcnt lgkmcnt(0)
	v_lshl_or_b32 v2, v1, 7, v51
	v_lshl_add_u64 v[10:11], s[4:5], 0, v[34:35]
	ds_read_b128 v[2:5], v2
	v_lshlrev_b32_e32 v6, 11, v1
	v_mov_b32_e32 v7, v0
	v_or_b32_e32 v14, 8, v1
	v_lshl_add_u64 v[12:13], v[10:11], 0, v[6:7]
	v_lshl_or_b32 v6, v14, 7, v51
	ds_read_b128 v[6:9], v6
	s_waitcnt lgkmcnt(1)
	global_store_dwordx4 v[12:13], v[2:5], off
	s_add_i32 s74, s74, 1
	s_cmp_eq_u32 s75, s0
	v_lshlrev_b32_e32 v2, 11, v14
	v_mov_b32_e32 v3, v0
	v_lshl_add_u64 v[2:3], v[10:11], 0, v[2:3]
	s_waitcnt lgkmcnt(0)
	global_store_dwordx4 v[2:3], v[6:9], off
	s_cselect_b64 s[4:5], -1, 0
	s_nop 0
	v_or_b32_e32 v6, 16, v1
	v_lshl_add_u32 v2, v6, 7, v51
	ds_read_b128 v[2:5], v2
	v_lshlrev_b32_e32 v6, 11, v6
	v_mov_b32_e32 v7, v0
	v_or_b32_e32 v1, 24, v1
	v_lshl_add_u64 v[12:13], v[10:11], 0, v[6:7]
	v_lshl_add_u32 v6, v1, 7, v51
	ds_read_b128 v[6:9], v6
	s_waitcnt lgkmcnt(1)
	global_store_dwordx4 v[12:13], v[2:5], off
	s_nop 1
	v_lshlrev_b32_e32 v2, 11, v1
	v_mov_b32_e32 v3, v0
	v_lshl_add_u64 v[2:3], v[10:11], 0, v[2:3]
	s_waitcnt lgkmcnt(0)
	global_store_dwordx4 v[2:3], v[6:9], off
	s_waitcnt lgkmcnt(0)
	s_waitcnt lgkmcnt(0)
	s_barrier

; __device__ __forceinline__ void xcd_barrier(const XcdBarrier& b) {
;     asm volatile("s_waitcnt vmcnt(0)" ::: "memory");
;     __syncthreads();
;     if (threadIdx.x == 0) {
;         unsigned* bar = b.bar;
;         __builtin_amdgcn_s_waitcnt(0);
;         unsigned nloc = b.st[0], nx = b.st[1];
;         if (nloc == 0u) { xcd_barrier_complete(bar, b.x, nloc, nx); b.st[0] = nloc; b.st[1] = nx; }
.LBB0_564:
	s_setprio 0
	s_waitcnt vmcnt(0)
	s_barrier
	s_mov_b64 s[4:5], exec
	v_readlane_b32 s0, v254, 3
	v_readlane_b32 s1, v254, 4
	s_and_b64 s[0:1], s[4:5], s[0:1]
	s_mov_b64 exec, s[0:1]
	s_cbranch_execz .LBB0_616
	v_mov_b32_e32 v0, 0x20200
	s_waitcnt vmcnt(0) expcnt(0) lgkmcnt(0)
	ds_read_b32 v2, v0
	v_mov_b32_e32 v0, 0x20204
	ds_read_b32 v0, v0
	s_waitcnt lgkmcnt(1)
	v_cmp_ne_u32_e32 vcc, 0, v2
	s_cbranch_vccnz .LBB0_580
	s_add_u32 s6, s30, 0x1bbc0200
	s_addc_u32 s7, s31, 0
	s_add_u32 s8, s30, 0x1bbc0400
	s_addc_u32 s9, s31, 0
	s_add_u32 s10, s30, 0x1bbc0500
	s_addc_u32 s11, s31, 0
	s_add_u32 s48, s30, 0x1bbc0600
	s_addc_u32 s49, s31, 0
	s_add_u32 s52, s30, 0x1bbc0700
	s_addc_u32 s53, s31, 0
	s_add_u32 s54, s30, 0x1bbc0800
	s_addc_u32 s55, s31, 0
	s_add_u32 s56, s30, 0x1bbc0900
	s_addc_u32 s57, s31, 0
	s_add_u32 s58, s30, 0x1bbc0a00
	s_addc_u32 s59, s31, 0
	s_add_u32 s60, s30, 0x1bbc0b00
	s_addc_u32 s61, s31, 0
	s_add_u32 s62, s30, 0x1bbc0c00
	s_addc_u32 s63, s31, 0
	s_add_u32 s64, s30, 0x1bbc0d00
	s_addc_u32 s65, s31, 0
	s_add_u32 s66, s30, 0x1bbc0e00
	s_addc_u32 s67, s31, 0
	s_add_u32 s70, s30, 0x1bbc0f00
	s_addc_u32 s71, s31, 0
	s_add_u32 s72, s30, 0x1bbc1000
	s_addc_u32 s73, s31, 0
	s_add_u32 s74, s30, 0x1bbc1100
	s_addc_u32 s75, s31, 0
	s_add_u32 s76, s30, 0x1bbc1200
	v_readlane_b32 s0, v254, 1
	s_addc_u32 s77, s31, 0
	s_mul_i32 s0, s35, s0
	s_add_u32 s78, s30, 0x1bbc1300
	s_mul_i32 s0, s0, s34
	s_addc_u32 s79, s31, 0
	s_mov_b32 s1, 1
	v_mov_b32_e32 v16, 0
	s_branch .LBB0_568

; #define FRESH_LANE() ({ int t_ = threadIdx.x; asm volatile("" : "+v"(t_)); t_ & 63; })
; template <int l> __device__ __forceinline__ void layer_body(const Args& a, unsigned char* lds, const XcdBarrier& bar, int G, int bx, int vcu, int gw, int NGW, int lane_, int tid_k, int wave) {
;     ...
;                 const int nun = 2048; const int per = (nun + G - 1) / G;
;                 const float lam = expf(wave_sum(a.lq1[FRESH_LANE()] * a.lk1[FRESH_LANE()])) - expf(wave_sum(a.lq2[FRESH_LANE()] * a.lk2[FRESH_LANE()])) + LAMBDA_INIT;
;                 int rot = 0; bool pre = false;
;                 for (int i = 0; i < per; ++i) {
;                     int g; bool ok = true; if (G == 256) g = (((vcu >> 5) * 4 + (i >> 1)) << 6) + (i & 1) * 32 + (vcu & 31); else { g = i * G + vcu; ok = g < nun; }
;                     int g2; bool ok2 = (i + 1 < per); if (G == 256) g2 = (((vcu >> 5) * 4 + ((i + 1) >> 1)) << 6) + ((i + 1) & 1) * 32 + (vcu & 31); else { g2 = (i + 1) * G + vcu; ok2 = ok2 && g2 < nun; }
.LBB0_1105:
	v_writelane_b32 v254, s0, 18
	v_writelane_b32 v254, s90, 15
	s_or_b64 exec, exec, s[6:7]
	s_waitcnt lgkmcnt(0)
	v_mov_b32_e32 v0, v222
	s_barrier
	v_mov_b32_e32 v1, v222
	v_and_b32_e32 v0, 63, v0
	v_lshlrev_b32_e32 v0, 2, v0
	global_load_dword v0, v0, s[16:17]
	v_mov_b32_e32 v2, v222
	v_and_b32_e32 v1, 63, v1
	v_lshlrev_b32_e32 v1, 2, v1
	global_load_dword v1, v1, s[18:19]
	v_mov_b32_e32 v3, v222
	v_and_b32_e32 v2, 63, v2
	v_lshlrev_b32_e32 v2, 2, v2
	global_load_dword v2, v2, s[20:21]
	v_mbcnt_hi_u32_b32 v4, -1, v223
	v_and_b32_e32 v3, 63, v3
	v_lshlrev_b32_e32 v3, 2, v3
	global_load_dword v3, v3, s[22:23]
	v_and_b32_e32 v5, 64, v4
	v_xor_b32_e32 v6, 1, v4
	v_add_u32_e32 v5, 64, v5
	v_cmp_lt_i32_e32 vcc, v6, v5
	v_xor_b32_e32 v7, 2, v4
	v_xor_b32_e32 v8, 4, v4
	v_cndmask_b32_e32 v6, v4, v6, vcc
	v_lshlrev_b32_e32 v223, 2, v6
	v_cmp_lt_i32_e32 vcc, v7, v5
	v_xor_b32_e32 v9, 8, v4
	v_xor_b32_e32 v10, 16, v4
	v_cndmask_b32_e32 v7, v4, v7, vcc
	v_lshlrev_b32_e32 v230, 2, v7
	v_cmp_lt_i32_e32 vcc, v8, v5
	s_add_i32 s1, s34, 0x7ff
	s_ashr_i32 s3, s1, 31
	v_cndmask_b32_e32 v8, v4, v8, vcc
	v_lshlrev_b32_e32 v231, 2, v8
	v_cmp_lt_i32_e32 vcc, v9, v5
	s_abs_i32 s1, s1
	s_mul_hi_u32 s4, s1, s95
	v_cndmask_b32_e32 v9, v4, v9, vcc
	v_lshlrev_b32_e32 v232, 2, v9
	v_cmp_lt_i32_e32 vcc, v10, v5
	s_mul_i32 s5, s4, s91
	s_sub_i32 s1, s1, s5
	v_cndmask_b32_e32 v7, v4, v10, vcc
	v_lshlrev_b32_e32 v233, 2, v7
	v_xor_b32_e32 v11, 32, v4
	s_xor_b32 s3, s3, s97
	s_add_i32 s6, s4, 1
	s_sub_i32 s5, s1, s91
	s_cmp_ge_u32 s1, s91
	v_cmp_lt_i32_e32 vcc, v11, v5
	s_cselect_b32 s4, s6, s4
	s_cselect_b32 s1, s5, s1
	s_add_i32 s5, s4, 1
	s_cmp_ge_u32 s1, s91
	s_cselect_b32 s1, s5, s4
	s_xor_b32 s1, s1, s3
	s_sub_i32 s5, s1, s3
	s_cmp_lt_i32 s5, 1
	s_mov_b32 s85, 0
	s_waitcnt vmcnt(2)
	v_mul_f32_e32 v6, v0, v1
	ds_bpermute_b32 v6, v223, v6
	s_waitcnt lgkmcnt(0)
	v_fmac_f32_e32 v6, v0, v1
	ds_bpermute_b32 v1, v230, v6
	s_waitcnt vmcnt(0)
	v_mul_f32_e32 v0, v2, v3
	ds_bpermute_b32 v0, v223, v0
	s_waitcnt lgkmcnt(1)
	v_add_f32_e32 v1, v6, v1
	s_waitcnt lgkmcnt(0)
	v_fmac_f32_e32 v0, v2, v3
	ds_bpermute_b32 v2, v231, v1
	ds_bpermute_b32 v3, v230, v0
	s_waitcnt lgkmcnt(1)
	v_add_f32_e32 v1, v1, v2
	s_waitcnt lgkmcnt(0)
	v_add_f32_e32 v0, v0, v3
	ds_bpermute_b32 v2, v232, v1
	ds_bpermute_b32 v3, v231, v0
	s_waitcnt lgkmcnt(1)
	v_add_f32_e32 v1, v1, v2
	s_waitcnt lgkmcnt(0)
	v_add_f32_e32 v2, v0, v3
	ds_bpermute_b32 v0, v233, v1
	ds_bpermute_b32 v3, v232, v2
	s_waitcnt lgkmcnt(1)
	v_add_f32_e32 v0, v1, v0
	s_waitcnt lgkmcnt(0)
	v_add_f32_e32 v1, v2, v3
	ds_bpermute_b32 v2, v233, v1
	v_cndmask_b32_e32 v3, v4, v11, vcc
	v_lshlrev_b32_e32 v234, 2, v3
	ds_bpermute_b32 v3, v234, v0
	s_waitcnt lgkmcnt(1)
	v_add_f32_e32 v1, v1, v2
	ds_bpermute_b32 v2, v234, v1
	s_cbranch_scc1 .LBB0_1181
	s_waitcnt lgkmcnt(1)
	v_add_f32_e32 v3, v0, v3
	s_mov_b32 s1, 0x3fb8aa3b
	v_mul_f32_e32 v0, 0x3fb8aa3b, v3
	v_fma_f32 v4, v3, s1, -v0
	v_rndne_f32_e32 v5, v0
	v_fmac_f32_e32 v4, 0x32a5705f, v3
	v_sub_f32_e32 v0, v0, v5
	v_add_f32_e32 v0, v0, v4
	v_exp_f32_e32 v0, v0
	v_cvt_i32_f32_e32 v4, v5
	s_waitcnt lgkmcnt(0)
	v_add_f32_e32 v1, v1, v2
	v_mul_f32_e32 v2, 0x3fb8aa3b, v1
	v_fma_f32 v5, v1, s1, -v2
	v_rndne_f32_e32 v6, v2
	s_cmpk_eq_i32 s34, 0x100
	s_mov_b32 s3, 0xc2ce8ed0
	v_fmac_f32_e32 v5, 0x32a5705f, v1
	v_sub_f32_e32 v2, v2, v6
	s_cselect_b64 s[0:1], -1, 0
	v_ldexp_f32 v4, v0, v4
	v_cmp_ngt_f32_e32 vcc, s3, v3
	s_mov_b32 s4, 0x42b17218
	v_add_f32_e32 v2, v2, v5
	v_writelane_b32 v254, s0, 12
	v_cndmask_b32_e32 v4, 0, v4, vcc
	v_exp_f32_e32 v2, v2
	v_cvt_i32_f32_e32 v5, v6
	v_mov_b32_e32 v6, 0x7f800000
	v_cmp_nlt_f32_e32 vcc, s4, v3
	v_writelane_b32 v254, s1, 13
	s_cmpk_lg_i32 s34, 0x100
	v_cndmask_b32_e32 v3, v6, v4, vcc
	v_cmp_ngt_f32_e32 vcc, s3, v1
	v_readlane_b32 s3, v254, 0
	s_cselect_b64 s[36:37], -1, 0
	s_lshr_b32 s1, s3, 3
	s_and_b32 s39, s1, 0x3fffffc
	s_and_b32 s43, s3, 31
	s_lshl_b32 s0, s94, 5
	v_ldexp_f32 v2, v2, v5
	s_add_u32 s40, s30, 0xf620800
	v_cndmask_b32_e32 v2, 0, v2, vcc
	v_cmp_nlt_f32_e32 vcc, s4, v1
	s_addc_u32 s41, s31, 0
	s_add_u32 s50, s30, 0xf621000
	v_cndmask_b32_e32 v1, v6, v2, vcc
	v_sub_f32_e32 v1, v3, v1
	s_addc_u32 s51, s31, 0
	v_add_f32_e32 v218, 0x3eb60549, v1
	s_add_u32 s52, s30, 0x12560800
	v_mov_b32_e32 v0, 0
	v_mov_b32_e32 v219, v218
	s_addc_u32 s53, s31, 0
	s_mov_b64 s[6:7], 0
	s_mov_b64 s[58:59], 0x60000
	s_mov_b64 s[60:61], 0xc0000
	s_mov_b64 s[62:63], 0x120000
	s_mov_b64 s[64:65], 0x60080
	s_mov_b32 s13, 0x41000000
	s_mov_b64 s[66:67], 0xc0080
	s_mov_b32 s14, 0xffff0000
	v_mov_b32_e32 v235, 0x358637bd
	v_mov_b32_e32 v236, 0x260
	s_mov_b32 s56, 0x3f24fd5c
	s_movk_i32 s57, 0x7fff
	s_mov_b32 s12, 0
	s_mov_b32 s9, 0
	v_writelane_b32 v254, s0, 14
	s_cmp_gt_u32 s94, 3
	s_cbranch_scc0 .Lprio_m2
	s_setprio 1
.Lprio_m2:
	s_branch .LBB0_1108
.LBB0_1107:
	s_mov_b64 s[6:7], 0
	s_cmp_eq_u32 s12, s5
	s_cbranch_scc1 .LBB0_1181

; __device__ __forceinline__ void xcd_barrier(const XcdBarrier& b) {
;     asm volatile("s_waitcnt vmcnt(0)" ::: "memory");
;     __syncthreads();
;     if (threadIdx.x == 0) {
;         unsigned* bar = b.bar;
;         __builtin_amdgcn_s_waitcnt(0);
;         unsigned nloc = b.st[0], nx = b.st[1];
;         if (nloc == 0u) { xcd_barrier_complete(bar, b.x, nloc, nx); b.st[0] = nloc; b.st[1] = nx; }
.LBB0_1181:
	s_setprio 0
	s_waitcnt vmcnt(0)
	s_waitcnt lgkmcnt(0)
	s_barrier
	s_mov_b64 s[6:7], exec
	v_readlane_b32 s4, v254, 3
	v_readlane_b32 s5, v254, 4
	v_readlane_b32 s84, v254, 16
	s_and_b64 s[4:5], s[6:7], s[4:5]
	v_readlane_b32 s82, v254, 15
	v_readlane_b32 s85, v254, 17
	v_readlane_b32 s0, v254, 18
	s_mov_b64 exec, s[4:5]
	s_cbranch_execz .LBB0_1233
	v_mov_b32_e32 v0, 0x20200
	s_waitcnt vmcnt(0) expcnt(0) lgkmcnt(0)
	ds_read_b32 v2, v0
	v_mov_b32_e32 v0, 0x20204
	ds_read_b32 v0, v0
	s_waitcnt lgkmcnt(1)
	v_cmp_ne_u32_e32 vcc, 0, v2
	s_cbranch_vccnz .LBB0_1197
	s_add_u32 s8, s30, 0x1bbc0200
	s_addc_u32 s9, s31, 0
	s_add_u32 s10, s30, 0x1bbc0400
	s_addc_u32 s11, s31, 0
	s_add_u32 s36, s30, 0x1bbc0500
	s_addc_u32 s37, s31, 0
	s_add_u32 s40, s30, 0x1bbc0600
	s_addc_u32 s41, s31, 0
	s_add_u32 s50, s30, 0x1bbc0700
	s_addc_u32 s51, s31, 0
	s_add_u32 s52, s30, 0x1bbc0800
	s_addc_u32 s53, s31, 0
	s_add_u32 s54, s30, 0x1bbc0900
	s_addc_u32 s55, s31, 0
	s_add_u32 s56, s30, 0x1bbc0a00
	s_addc_u32 s57, s31, 0
	s_add_u32 s58, s30, 0x1bbc0b00
	s_addc_u32 s59, s31, 0
	s_add_u32 s60, s30, 0x1bbc0c00
	s_addc_u32 s61, s31, 0
	s_add_u32 s62, s30, 0x1bbc0d00
	s_addc_u32 s63, s31, 0
	s_add_u32 s64, s30, 0x1bbc0e00
	s_addc_u32 s65, s31, 0
	s_add_u32 s66, s30, 0x1bbc0f00
	s_addc_u32 s67, s31, 0
	s_add_u32 s68, s30, 0x1bbc1000
	s_addc_u32 s69, s31, 0
	s_add_u32 s70, s30, 0x1bbc1100
	s_addc_u32 s71, s31, 0
	s_add_u32 s72, s30, 0x1bbc1200
	v_readlane_b32 s1, v254, 1
	s_addc_u32 s73, s31, 0
	s_mul_i32 s1, s35, s1
	s_add_u32 s74, s30, 0x1bbc1300
	s_mul_i32 s1, s1, s34
	s_addc_u32 s75, s31, 0
	s_mov_b32 s3, 1
	v_mov_b32_e32 v16, 0
	s_branch .LBB0_1185
